# A3 selection-mask application rewritten: v_bfe_i32+v_bfi_b32 (2 VALU per element, no vcc) instead of and/cmp/cndmask+nop
# speedup vs baseline: 1.0251x; 1.0062x over previous
; #define LAS __attribute__((address_space(3)))
; #define MFMA32(a, b, c) __builtin_amdgcn_mfma_f32_32x32x16_bf16((a), (b), (c), 0, 0, 0)
;     ...
;             if (MODE == 0) {
; #pragma unroll
;                 for (int w = 0; w < NKB / 2; ++w) mw[w] = MASK64[(rowbase + q0 + r) * 32 + (key0 >> 6) + w];
;             }
;             f32x16 sv[NKB];
; #pragma unroll
;             for (int kb2 = 0; kb2 < NKB; ++kb2)
; #pragma unroll
;                 for (int i = 0; i < 16; ++i) sv[kb2][i] = nm_run;
;             const LAS unsigned char* kb_ = lds + st * STAGE + koff + sub * 32 * NKB * KP;
; #pragma unroll
;             for (int kh = 0; kh < 2; ++kh) {
;                 bf16x8 kfr[2][NKB];
; #pragma unroll
;                 for (int k2 = 0; k2 < 2; ++k2)
; #pragma unroll
;                     for (int kb2 = 0; kb2 < NKB; ++kb2) kfr[k2][kb2] = *(const LAS bf16x8*)(kb_ + (32 * kb2 + r) * KP + (2 * kh + k2) * 32 + h * 16);
;                 if (NKB == 2) asm volatile("" : "+v"(kfr[0][0]), "+v"(kfr[0][1]), "+v"(kfr[1][0]), "+v"(kfr[1][1]));
;                 else asm volatile("" : "+v"(kfr[0][0]), "+v"(kfr[0][1]), "+v"(kfr[0][NKB - 2]), "+v"(kfr[0][NKB - 1]), "+v"(kfr[1][0]), "+v"(kfr[1][1]), "+v"(kfr[1][NKB - 2]), "+v"(kfr[1][NKB - 1]));
; #pragma unroll
;                 for (int k2 = 0; k2 < 2; ++k2)
; #pragma unroll
;                     for (int kb2 = 0; kb2 < NKB; ++kb2) sv[kb2] = MFMA32(kfr[k2][kb2], qf[2 * kh + k2], sv[kb2]);
;             }
;             if (MODE == 0) {
; #pragma unroll
;                 for (int kb2 = 0; kb2 < NKB; ++kb2) {
;                     const unsigned wsel = ((kb2 & 1) ? (unsigned)(mw[kb2 >> 1] >> 32) : (unsigned)mw[kb2 >> 1]) >> (4 * h);
; #pragma unroll
;                     for (int i = 0; i < 16; ++i) { const int cb = (i & 3) + 8 * (i >> 2); if (!((wsel >> cb) & 1u)) sv[kb2][i] = -1e30f; }
;                 }
.LBB0_522:
	v_lshl_add_u64 v[34:35], s[0:1], 0, v[166:167]
	v_add_co_u32_e32 v34, vcc, 0x1d600000, v34
	s_and_b32 s7, s6, 1
	s_nop 0
	v_addc_co_u32_e32 v35, vcc, 0, v35, vcc
	global_load_dwordx4 v[132:135], v[34:35], off
	s_mul_i32 s9, s7, 0x8a00
	s_add_i32 s9, s9, 0
	v_add3_u32 v185, s9, v180, v182
	ds_read_b128 v[186:189], v185 offset:13856
	ds_read_b128 v[190:193], v185 offset:9248
	ds_read_b128 v[200:203], v185 offset:4640
	ds_read_b128 v[204:207], v185 offset:13824
	ds_read_b128 v[208:211], v185 offset:9216
	ds_read_b128 v[48:51], v185 offset:4608
	ds_read_b128 v[52:55], v185
	ds_read_b128 v[212:215], v185 offset:32
	v_mov_b32_e32 v33, v32
	v_mov_b32_e32 v34, v32
	v_mov_b32_e32 v35, v32
	v_mov_b32_e32 v36, v32
	v_mov_b32_e32 v37, v32
	v_mov_b32_e32 v38, v32
	v_mov_b32_e32 v39, v32
	v_mov_b32_e32 v40, v32
	v_mov_b32_e32 v41, v32
	v_mov_b32_e32 v42, v32
	v_mov_b32_e32 v43, v32
	v_mov_b32_e32 v44, v32
	v_mov_b32_e32 v45, v32
	v_mov_b32_e32 v46, v32
	v_mov_b32_e32 v47, v32
	s_waitcnt lgkmcnt(0)
	s_nop 0
	v_mfma_f32_32x32x16_bf16 v[82:97], v[52:55], v[100:103], v[32:47]
	v_mfma_f32_32x32x16_bf16 v[66:81], v[48:51], v[100:103], v[32:47]
	v_mfma_f32_32x32x16_bf16 v[50:65], v[208:211], v[100:103], v[32:47]
	v_mov_b64_e32 v[48:49], v[46:47]
	s_nop 5
	v_mov_b64_e32 v[46:47], v[44:45]
	v_mov_b64_e32 v[44:45], v[42:43]
	v_mov_b64_e32 v[42:43], v[40:41]
	v_mov_b64_e32 v[40:41], v[38:39]
	v_mov_b64_e32 v[38:39], v[36:37]
	v_mov_b64_e32 v[36:37], v[34:35]
	v_mov_b64_e32 v[34:35], v[32:33]
	v_mfma_f32_32x32x16_bf16 v[82:97], v[212:215], v[104:107], v[82:97]
	s_waitcnt vmcnt(0)
	v_lshrrev_b32_e32 v132, v150, v132
	v_lshrrev_b32_e32 v133, v150, v133
	v_lshrrev_b32_e32 v134, v150, v134
	v_lshrrev_b32_e32 v135, v150, v135
	v_mfma_f32_32x32x16_bf16 v[34:49], v[204:207], v[100:103], v[34:49]
	v_mfma_f32_32x32x16_bf16 v[66:81], v[200:203], v[104:107], v[66:81]
	v_mfma_f32_32x32x16_bf16 v[50:65], v[190:193], v[104:107], v[50:65]
	v_mfma_f32_32x32x16_bf16 v[34:49], v[186:189], v[104:107], v[34:49]
	ds_read_b128 v[186:189], v185 offset:13920
	ds_read_b128 v[190:193], v185 offset:9312
	ds_read_b128 v[200:203], v185 offset:4704
	ds_read_b128 v[204:207], v185 offset:13888
	ds_read_b128 v[208:211], v185 offset:9280
	ds_read_b128 v[212:215], v185 offset:4672
	ds_read_b128 v[216:219], v185 offset:64
	ds_read_b128 v[220:223], v185 offset:96
	s_waitcnt lgkmcnt(0)
	s_nop 0
	v_mfma_f32_32x32x16_bf16 v[82:97], v[216:219], v[108:111], v[82:97]
	v_mfma_f32_32x32x16_bf16 v[82:97], v[220:223], v[112:115], v[82:97]
	v_mfma_f32_32x32x16_bf16 v[66:81], v[212:215], v[108:111], v[66:81]
	s_nop 10
	v_bfe_i32 v224, v132, 0, 1
	v_bfi_b32 v82, v224, v82, v235
	v_bfe_i32 v224, v132, 1, 1
	v_bfi_b32 v83, v224, v83, v235
	v_mfma_f32_32x32x16_bf16 v[66:81], v[200:203], v[112:115], v[66:81]
	v_bfe_i32 v224, v132, 2, 1
	v_bfi_b32 v84, v224, v84, v235
	v_bfe_i32 v224, v132, 3, 1
	v_bfi_b32 v85, v224, v85, v235
	v_mfma_f32_32x32x16_bf16 v[50:65], v[208:211], v[108:111], v[50:65]
	v_bfe_i32 v224, v132, 8, 1
	v_bfi_b32 v86, v224, v86, v235
	v_bfe_i32 v224, v132, 9, 1
	v_bfi_b32 v87, v224, v87, v235
	v_mfma_f32_32x32x16_bf16 v[50:65], v[190:193], v[112:115], v[50:65]
	v_bfe_i32 v224, v132, 10, 1
	v_bfi_b32 v88, v224, v88, v235
	v_bfe_i32 v224, v132, 11, 1
	v_bfi_b32 v89, v224, v89, v235
	v_mfma_f32_32x32x16_bf16 v[34:49], v[204:207], v[108:111], v[34:49]
	v_bfe_i32 v224, v132, 16, 1
	v_bfi_b32 v90, v224, v90, v235
	v_bfe_i32 v224, v132, 17, 1
	v_bfi_b32 v91, v224, v91, v235
	v_mfma_f32_32x32x16_bf16 v[34:49], v[186:189], v[112:115], v[34:49]
	v_bfe_i32 v224, v132, 18, 1
	v_bfi_b32 v92, v224, v92, v235
	v_bfe_i32 v224, v132, 19, 1
	v_bfi_b32 v93, v224, v93, v235
	v_bfe_i32 v224, v132, 24, 1
	v_bfi_b32 v94, v224, v94, v235
	v_bfe_i32 v224, v132, 25, 1
	v_bfi_b32 v95, v224, v95, v235
	v_bfe_i32 v224, v132, 26, 1
	v_bfi_b32 v96, v224, v96, v235
	v_bfe_i32 v224, v132, 27, 1
	v_bfi_b32 v97, v224, v97, v235
	v_bfe_i32 v224, v133, 0, 1
	v_bfi_b32 v66, v224, v66, v235
	v_bfe_i32 v224, v133, 1, 1
	v_bfi_b32 v67, v224, v67, v235
	v_bfe_i32 v224, v133, 2, 1
	v_bfi_b32 v68, v224, v68, v235
	v_bfe_i32 v224, v133, 3, 1
	v_bfi_b32 v69, v224, v69, v235
	v_bfe_i32 v224, v133, 8, 1
	v_bfi_b32 v70, v224, v70, v235
	v_bfe_i32 v224, v133, 9, 1
	v_bfi_b32 v71, v224, v71, v235
	v_bfe_i32 v224, v133, 10, 1
	v_bfi_b32 v72, v224, v72, v235
	v_bfe_i32 v224, v133, 11, 1
	v_bfi_b32 v73, v224, v73, v235
	v_bfe_i32 v224, v133, 16, 1
	v_bfi_b32 v74, v224, v74, v235
	v_bfe_i32 v224, v133, 17, 1
	v_bfi_b32 v75, v224, v75, v235
	v_bfe_i32 v224, v133, 18, 1
	v_bfi_b32 v76, v224, v76, v235
	v_bfe_i32 v224, v133, 19, 1
	v_bfi_b32 v77, v224, v77, v235
	v_bfe_i32 v224, v133, 24, 1
	v_bfi_b32 v78, v224, v78, v235
	v_bfe_i32 v224, v133, 25, 1
	v_bfi_b32 v79, v224, v79, v235
	v_bfe_i32 v224, v133, 26, 1
	v_bfi_b32 v80, v224, v80, v235
	v_bfe_i32 v224, v133, 27, 1
	v_bfi_b32 v81, v224, v81, v235
	v_bfe_i32 v224, v134, 0, 1
	v_bfi_b32 v50, v224, v50, v235
	v_bfe_i32 v224, v134, 1, 1
	v_bfi_b32 v51, v224, v51, v235
	v_bfe_i32 v224, v134, 2, 1
	v_bfi_b32 v52, v224, v52, v235
	v_bfe_i32 v224, v134, 3, 1
	v_bfi_b32 v53, v224, v53, v235
	v_bfe_i32 v224, v134, 8, 1
	v_bfi_b32 v54, v224, v54, v235
	v_bfe_i32 v224, v134, 9, 1
	v_bfi_b32 v55, v224, v55, v235
	v_bfe_i32 v224, v134, 10, 1
	v_bfi_b32 v56, v224, v56, v235
	v_bfe_i32 v224, v134, 11, 1
	v_bfi_b32 v57, v224, v57, v235
	v_bfe_i32 v224, v134, 16, 1
	v_bfi_b32 v58, v224, v58, v235
	v_bfe_i32 v224, v134, 17, 1
	v_bfi_b32 v59, v224, v59, v235
	v_bfe_i32 v224, v134, 18, 1
	v_bfi_b32 v60, v224, v60, v235
	v_bfe_i32 v224, v134, 19, 1
	v_bfi_b32 v61, v224, v61, v235
	v_bfe_i32 v224, v134, 24, 1
; DI float shx(float v, int o, int lane) { return __int_as_float(__builtin_amdgcn_ds_bpermute((lane ^ o) << 2, __float_as_int(v))); }
; DI int crow(int i, int h) { return (i & 3) + 8 * (i >> 2) + 4 * h; }
;     ...
;                     for (int i = 0; i < 16; ++i) { const int cb = (i & 3) + 8 * (i >> 2); if (!((wsel >> cb) & 1u)) sv[kb2][i] = -1e30f; }
;                 }
;             } else if (key0 + 32 * NKB - 1 > q0) {
;                 const int qq = q0 + r;
; #pragma unroll
;                 for (int kb2 = 0; kb2 < NKB; ++kb2)
; #pragma unroll
;                     for (int i = 0; i < 16; ++i) { if (key0 + 32 * kb2 + crow(i, h) > qq) sv[kb2][i] = -1e30f; }
;             }
;             float mx = -1e30f;
; #pragma unroll
;             for (int kb2 = 0; kb2 < NKB; ++kb2)
; #pragma unroll
;                 for (int i = 0; i < 16; ++i) mx = __builtin_fmaxf(mx, sv[kb2][i]);
;             mx = __builtin_fmaxf(mx, shx(mx, 32, lane));
;             if (__ballot(mx > 8.0f)) {
;                 const float delta = __builtin_fmaxf(mx, 0.f);
;                 const float alpha = __builtin_amdgcn_exp2f(-delta);
;                 nm_run -= delta; l_run *= alpha;
; #pragma unroll
;                 for (int kb2 = 0; kb2 < NKB; ++kb2)
; #pragma unroll
;                     for (int i = 0; i < 16; ++i) sv[kb2][i] -= delta;
; #pragma unroll
;                 for (int db = 0; db < NDB; ++db)
; #pragma unroll
;                     for (int i = 0; i < 16; ++i) ot[db][i] *= alpha;
;             }
	v_bfi_b32 v62, v224, v62, v235
	v_bfe_i32 v224, v134, 25, 1
	v_bfi_b32 v63, v224, v63, v235
	v_bfe_i32 v224, v134, 26, 1
	v_bfi_b32 v64, v224, v64, v235
	v_bfe_i32 v224, v134, 27, 1
	v_bfi_b32 v65, v224, v65, v235
	v_bfe_i32 v224, v135, 0, 1
	v_bfi_b32 v34, v224, v34, v235
	v_bfe_i32 v224, v135, 1, 1
	v_bfi_b32 v35, v224, v35, v235
	v_bfe_i32 v224, v135, 2, 1
	v_bfi_b32 v36, v224, v36, v235
	v_bfe_i32 v224, v135, 3, 1
	v_bfi_b32 v37, v224, v37, v235
	v_bfe_i32 v224, v135, 8, 1
	v_bfi_b32 v38, v224, v38, v235
	v_bfe_i32 v224, v135, 9, 1
	v_bfi_b32 v39, v224, v39, v235
	v_bfe_i32 v224, v135, 10, 1
	v_bfi_b32 v40, v224, v40, v235
	v_bfe_i32 v224, v135, 11, 1
	v_bfi_b32 v41, v224, v41, v235
	v_bfe_i32 v224, v135, 16, 1
	v_bfi_b32 v42, v224, v42, v235
	v_bfe_i32 v224, v135, 17, 1
	v_bfi_b32 v43, v224, v43, v235
	v_bfe_i32 v224, v135, 18, 1
	v_bfi_b32 v44, v224, v44, v235
	v_bfe_i32 v224, v135, 19, 1
	v_bfi_b32 v45, v224, v45, v235
	v_bfe_i32 v224, v135, 24, 1
	v_bfi_b32 v46, v224, v46, v235
	v_bfe_i32 v224, v135, 25, 1
	v_bfi_b32 v47, v224, v47, v235
	v_bfe_i32 v224, v135, 26, 1
	v_bfi_b32 v48, v224, v48, v235
	v_max3_f32 v33, v82, s61, v83
	v_max3_f32 v33, v33, v84, v85
	v_max3_f32 v33, v33, v86, v87
	v_max3_f32 v33, v33, v88, v89
	v_max3_f32 v33, v33, v90, v91
	v_max3_f32 v33, v33, v92, v93
	v_max3_f32 v33, v33, v94, v95
	v_max3_f32 v33, v33, v96, v97
	v_max3_f32 v33, v33, v66, v67
	v_max3_f32 v33, v33, v68, v69
	v_max3_f32 v33, v33, v70, v71
	v_max3_f32 v33, v33, v72, v73
	v_max3_f32 v33, v33, v74, v75
	v_max3_f32 v33, v33, v76, v77
	v_max3_f32 v33, v33, v78, v79
	v_max3_f32 v33, v33, v80, v81
	v_max3_f32 v33, v33, v50, v51
	v_max3_f32 v33, v33, v52, v53
	v_max3_f32 v33, v33, v54, v55
	v_max3_f32 v33, v33, v56, v57
	v_max3_f32 v33, v33, v58, v59
	v_max3_f32 v33, v33, v60, v61
	v_max3_f32 v33, v33, v62, v63
	v_max3_f32 v33, v33, v64, v65
	v_max3_f32 v33, v33, v34, v35
	v_max3_f32 v33, v33, v36, v37
	v_max3_f32 v33, v33, v38, v39
	v_max3_f32 v33, v33, v40, v41
	v_max3_f32 v33, v33, v42, v43
	v_max3_f32 v33, v33, v44, v45
	v_bfe_i32 v224, v135, 27, 1
	v_bfi_b32 v49, v224, v49, v235
	v_max3_f32 v33, v33, v46, v47
	v_max3_f32 v33, v33, v48, v49
	ds_bpermute_b32 v132, v181, v33
	s_waitcnt lgkmcnt(0)
	v_max_f32_e32 v132, v132, v132
	v_max_f32_e32 v33, v33, v132
	v_cmp_lt_f32_e32 vcc, s33, v33
	s_cbranch_vccz .LBB0_524
	v_max_f32_e32 v33, v33, v33
	v_max_f32_e32 v132, 0, v33
	v_exp_f32_e64 v134, -v132
	v_sub_f32_e32 v32, v32, v132
	v_pk_add_f32 v[82:83], v[82:83], v[132:133] op_sel_hi:[1,0] neg_lo:[0,1] neg_hi:[0,1]
	v_pk_add_f32 v[84:85], v[84:85], v[132:133] op_sel_hi:[1,0] neg_lo:[0,1] neg_hi:[0,1]
	v_pk_add_f32 v[86:87], v[86:87], v[132:133] op_sel_hi:[1,0] neg_lo:[0,1] neg_hi:[0,1]
	v_pk_add_f32 v[88:89], v[88:89], v[132:133] op_sel_hi:[1,0] neg_lo:[0,1] neg_hi:[0,1]
	v_pk_add_f32 v[90:91], v[90:91], v[132:133] op_sel_hi:[1,0] neg_lo:[0,1] neg_hi:[0,1]
	v_pk_add_f32 v[92:93], v[92:93], v[132:133] op_sel_hi:[1,0] neg_lo:[0,1] neg_hi:[0,1]
	v_pk_add_f32 v[94:95], v[94:95], v[132:133] op_sel_hi:[1,0] neg_lo:[0,1] neg_hi:[0,1]
	v_pk_add_f32 v[96:97], v[96:97], v[132:133] op_sel_hi:[1,0] neg_lo:[0,1] neg_hi:[0,1]
	v_pk_add_f32 v[66:67], v[66:67], v[132:133] op_sel_hi:[1,0] neg_lo:[0,1] neg_hi:[0,1]
	v_pk_add_f32 v[68:69], v[68:69], v[132:133] op_sel_hi:[1,0] neg_lo:[0,1] neg_hi:[0,1]
	v_pk_add_f32 v[70:71], v[70:71], v[132:133] op_sel_hi:[1,0] neg_lo:[0,1] neg_hi:[0,1]
	v_pk_add_f32 v[72:73], v[72:73], v[132:133] op_sel_hi:[1,0] neg_lo:[0,1] neg_hi:[0,1]
	v_pk_add_f32 v[74:75], v[74:75], v[132:133] op_sel_hi:[1,0] neg_lo:[0,1] neg_hi:[0,1]
	v_pk_add_f32 v[76:77], v[76:77], v[132:133] op_sel_hi:[1,0] neg_lo:[0,1] neg_hi:[0,1]
	v_pk_add_f32 v[78:79], v[78:79], v[132:133] op_sel_hi:[1,0] neg_lo:[0,1] neg_hi:[0,1]
	v_pk_add_f32 v[80:81], v[80:81], v[132:133] op_sel_hi:[1,0] neg_lo:[0,1] neg_hi:[0,1]
	v_pk_add_f32 v[50:51], v[50:51], v[132:133] op_sel_hi:[1,0] neg_lo:[0,1] neg_hi:[0,1]
	v_pk_add_f32 v[52:53], v[52:53], v[132:133] op_sel_hi:[1,0] neg_lo:[0,1] neg_hi:[0,1]
	v_pk_add_f32 v[54:55], v[54:55], v[132:133] op_sel_hi:[1,0] neg_lo:[0,1] neg_hi:[0,1]
	v_pk_add_f32 v[56:57], v[56:57], v[132:133] op_sel_hi:[1,0] neg_lo:[0,1] neg_hi:[0,1]
	v_pk_add_f32 v[58:59], v[58:59], v[132:133] op_sel_hi:[1,0] neg_lo:[0,1] neg_hi:[0,1]
	v_pk_add_f32 v[60:61], v[60:61], v[132:133] op_sel_hi:[1,0] neg_lo:[0,1] neg_hi:[0,1]
	v_pk_add_f32 v[62:63], v[62:63], v[132:133] op_sel_hi:[1,0] neg_lo:[0,1] neg_hi:[0,1]
	v_pk_add_f32 v[64:65], v[64:65], v[132:133] op_sel_hi:[1,0] neg_lo:[0,1] neg_hi:[0,1]
	v_pk_add_f32 v[34:35], v[34:35], v[132:133] op_sel_hi:[1,0] neg_lo:[0,1] neg_hi:[0,1]
	v_pk_add_f32 v[36:37], v[36:37], v[132:133] op_sel_hi:[1,0] neg_lo:[0,1] neg_hi:[0,1]
	v_pk_add_f32 v[38:39], v[38:39], v[132:133] op_sel_hi:[1,0] neg_lo:[0,1] neg_hi:[0,1]
	v_pk_add_f32 v[40:41], v[40:41], v[132:133] op_sel_hi:[1,0] neg_lo:[0,1] neg_hi:[0,1]
	v_pk_add_f32 v[42:43], v[42:43], v[132:133] op_sel_hi:[1,0] neg_lo:[0,1] neg_hi:[0,1]
	v_pk_add_f32 v[44:45], v[44:45], v[132:133] op_sel_hi:[1,0] neg_lo:[0,1] neg_hi:[0,1]
	v_pk_add_f32 v[46:47], v[46:47], v[132:133] op_sel_hi:[1,0] neg_lo:[0,1] neg_hi:[0,1]
	v_pk_add_f32 v[48:49], v[48:49], v[132:133] op_sel_hi:[1,0] neg_lo:[0,1] neg_hi:[0,1]
	v_pk_mul_f32 v[14:15], v[14:15], v[134:135] op_sel_hi:[1,0]
	v_pk_mul_f32 v[12:13], v[12:13], v[134:135] op_sel_hi:[1,0]
	v_pk_mul_f32 v[10:11], v[10:11], v[134:135] op_sel_hi:[1,0]
	v_pk_mul_f32 v[8:9], v[8:9], v[134:135] op_sel_hi:[1,0]
	v_pk_mul_f32 v[6:7], v[6:7], v[134:135] op_sel_hi:[1,0]
	v_pk_mul_f32 v[4:5], v[4:5], v[134:135] op_sel_hi:[1,0]
	v_pk_mul_f32 v[2:3], v[2:3], v[134:135] op_sel_hi:[1,0]
	v_pk_mul_f32 v[0:1], v[0:1], v[134:135] op_sel_hi:[1,0]
	v_pk_mul_f32 v[30:31], v[30:31], v[134:135] op_sel_hi:[1,0]
	v_pk_mul_f32 v[28:29], v[28:29], v[134:135] op_sel_hi:[1,0]
	v_pk_mul_f32 v[26:27], v[26:27], v[134:135] op_sel_hi:[1,0]
	v_pk_mul_f32 v[24:25], v[24:25], v[134:135] op_sel_hi:[1,0]
	v_pk_mul_f32 v[22:23], v[22:23], v[134:135] op_sel_hi:[1,0]
	v_pk_mul_f32 v[20:21], v[20:21], v[134:135] op_sel_hi:[1,0]
	v_pk_mul_f32 v[18:19], v[18:19], v[134:135] op_sel_hi:[1,0]
	v_pk_mul_f32 v[16:17], v[16:17], v[134:135] op_sel_hi:[1,0]
	v_mul_f32_e32 v184, v184, v134
